# PR2: s_setprio 2 for small-work waves 0-3 in phase 0 and streaming waves 4-7 in phase 1 (inverse of PR1)
# speedup vs baseline: 1.0019x; 1.0019x over previous
; __device__ void p0_xconv(const Args& a) {
;     f16* XH = (f16*)(a.ws + WS_XH); float* SS = (float*)(a.ws + WS_SS);
;     int tid_ = threadIdx.x; asm volatile("" : "+v"(tid_));
;     const int lane = tid_ & 63, wv = tid_ >> 6;
;     const int nwv = (int)gridDim.x * 8;
;     for (int row0 = (int)blockIdx.x * 8 + wv; row0 < MROWS; row0 += 4 * nwv) {
.LBB0_13:
	s_or_b64 exec, exec, s[4:5]
	v_readfirstlane_b32 s100, v0
	s_nop 3
	s_cmp_ge_u32 s100, 0x100
	s_cbranch_scc1 .Lws_x
	s_mov_b32 s101, 0
	s_setprio 2

; __device__ void p0_xconv(const Args& a) {
;     ...
;     }
; }
.Lws_done:
	s_setprio 0
	v_add_u32_e32 v0, 0xffffff00, v0
	s_branch .LBB0_37

; __device__ void p0_xconv(const Args& a) {
;     ...
;     const int lane = tid_ & 63, wv = tid_ >> 6;
;     const int nwv = (int)gridDim.x * 8;
;     for (int row0 = (int)blockIdx.x * 8 + wv; row0 < MROWS; row0 += 4 * nwv) {
;         f32x4 v[4][4];
; #pragma unroll
;         for (int r = 0; r < 4; ++r) {
;             const int row = row0 + r * nwv;
;             if (row < MROWS) {
;                 const float* src = (row < ROWS_PROMPT) ? a.x_prompt + (size_t)row * DM : a.x_sample + (size_t)(row - ROWS_PROMPT) * DM;
; #pragma unroll
;                 for (int i = 0; i < 4; ++i) v[r][i] = __builtin_nontemporal_load((const f32x4*)(src + i * 256 + lane * 4));
;             }
;         }
; #pragma unroll
;         for (int r = 0; r < 4; ++r) {
;             const int row = row0 + r * nwv;
;             if (row < MROWS) {
;                 float ss = 0.f;
; #pragma unroll
;                 for (int i = 0; i < 4; ++i) {
;                     const f32x4 x = v[r][i];
;                     ss += (x[0] * x[0] + x[1] * x[1]) + (x[2] * x[2] + x[3] * x[3]);
;                     f16x4 h; h[0] = (f16)x[0]; h[1] = (f16)x[1]; h[2] = (f16)x[2]; h[3] = (f16)x[3];
;                     *(f16x4*)(XH + (size_t)row * DM + i * 256 + lane * 4) = h;
.Lpw_x:
	s_setprio 2
	s_barrier
	v_and_b32_e32 v136, 63, v0
	v_lshrrev_b32_e32 v137, 6, v0
	s_nop 0
	v_readfirstlane_b32 s3, v137
	s_nop 3
	s_lshl_b32 s4, s2, 2
	s_add_i32 s3, s3, s4
	s_add_i32 s3, s3, -4
	s_mov_b64 s[12:13], 1
	v_xor_b32_e32 v130, 1, v136
	v_lshlrev_b32_e32 v130, 2, v130
	v_xor_b32_e32 v131, 2, v136
	v_lshlrev_b32_e32 v131, 2, v131
	v_xor_b32_e32 v132, 4, v136
	v_lshlrev_b32_e32 v132, 2, v132
	v_xor_b32_e32 v133, 8, v136
	v_lshlrev_b32_e32 v133, 2, v133
	v_xor_b32_e32 v134, 16, v136
	v_lshlrev_b32_e32 v134, 2, v134
	v_xor_b32_e32 v135, 32, v136
	v_lshlrev_b32_e32 v135, 2, v135
	v_lshlrev_b32_e32 v140, 4, v136
	v_lshlrev_b32_e32 v144, 3, v136
	v_lshlrev_b32_e32 v186, 2, v136
	v_lshlrev_b32_e32 v141, 4, v136
	v_add_u32_e32 v141, 0x400000, v141
	v_lshlrev_b32_e32 v145, 3, v136
	v_add_u32_e32 v145, 0x200000, v145
	v_lshlrev_b32_e32 v187, 2, v136
	v_add_u32_e32 v187, 0x10000, v187
	v_lshlrev_b32_e32 v142, 4, v136
	v_add_u32_e32 v142, 0x800000, v142
	v_lshlrev_b32_e32 v146, 3, v136
	v_add_u32_e32 v146, 0x400000, v146
	v_lshlrev_b32_e32 v188, 2, v136
	v_add_u32_e32 v188, 0x20000, v188
	v_lshlrev_b32_e32 v143, 4, v136
	v_add_u32_e32 v143, 0xc00000, v143
	v_lshlrev_b32_e32 v147, 3, v136
	v_add_u32_e32 v147, 0x600000, v147
	v_lshlrev_b32_e32 v189, 2, v136
	v_add_u32_e32 v189, 0x30000, v189
	s_add_i32 s6, s3, 0x4000
	s_lshl_b32 s6, s6, 12
	s_add_u32 s4, s18, s6
	s_addc_u32 s5, s19, 0
	global_load_dwordx4 v[2:5], v140, s[4:5] nt
	global_load_dwordx4 v[6:9], v140, s[4:5] offset:1024 nt
	global_load_dwordx4 v[10:13], v140, s[4:5] offset:2048 nt
	global_load_dwordx4 v[14:17], v140, s[4:5] offset:3072 nt
	global_load_dwordx4 v[18:21], v141, s[4:5] nt
	global_load_dwordx4 v[22:25], v141, s[4:5] offset:1024 nt
	global_load_dwordx4 v[26:29], v141, s[4:5] offset:2048 nt
	global_load_dwordx4 v[30:33], v141, s[4:5] offset:3072 nt
	global_load_dwordx4 v[34:37], v142, s[4:5] nt
	global_load_dwordx4 v[38:41], v142, s[4:5] offset:1024 nt
	global_load_dwordx4 v[42:45], v142, s[4:5] offset:2048 nt
	global_load_dwordx4 v[46:49], v142, s[4:5] offset:3072 nt
	global_load_dwordx4 v[50:53], v143, s[4:5] nt
	global_load_dwordx4 v[54:57], v143, s[4:5] offset:1024 nt
	global_load_dwordx4 v[58:61], v143, s[4:5] offset:2048 nt
	global_load_dwordx4 v[62:65], v143, s[4:5] offset:3072 nt
	s_add_i32 s6, s3, 0x5000
	s_lshl_b32 s6, s6, 12
	s_add_u32 s4, s18, s6
	s_addc_u32 s5, s19, 0
	global_load_dwordx4 v[66:69], v140, s[4:5] nt
	global_load_dwordx4 v[70:73], v140, s[4:5] offset:1024 nt
	global_load_dwordx4 v[74:77], v140, s[4:5] offset:2048 nt
	global_load_dwordx4 v[78:81], v140, s[4:5] offset:3072 nt
	global_load_dwordx4 v[82:85], v141, s[4:5] nt
	global_load_dwordx4 v[86:89], v141, s[4:5] offset:1024 nt
	global_load_dwordx4 v[90:93], v141, s[4:5] offset:2048 nt
	global_load_dwordx4 v[94:97], v141, s[4:5] offset:3072 nt
	global_load_dwordx4 v[98:101], v142, s[4:5] nt
	global_load_dwordx4 v[102:105], v142, s[4:5] offset:1024 nt
	global_load_dwordx4 v[106:109], v142, s[4:5] offset:2048 nt
	global_load_dwordx4 v[110:113], v142, s[4:5] offset:3072 nt
	global_load_dwordx4 v[114:117], v143, s[4:5] nt
	global_load_dwordx4 v[118:121], v143, s[4:5] offset:1024 nt
	global_load_dwordx4 v[122:125], v143, s[4:5] offset:2048 nt
	global_load_dwordx4 v[126:129], v143, s[4:5] offset:3072 nt
	s_waitcnt vmcnt(16)
	s_add_i32 s6, s3, 0x8000
	s_lshl_b32 s7, s6, 11
	s_add_u32 s10, s40, s7
	s_addc_u32 s11, s41, 0
	s_lshl_b32 s7, s6, 6
	s_add_u32 s6, s40, s7
	s_addc_u32 s7, s41, 0
	s_add_u32 s6, s6, 0x1f800000
	s_addc_u32 s7, s7, 0
	v_mul_f32_e32 v150, v3, v3
	v_mul_f32_e32 v151, v5, v5
	v_fmac_f32_e32 v150, v2, v2
	v_fmac_f32_e32 v151, v4, v4
	v_add_f32_e32 v160, v150, v151
	v_cvt_pk_f16_f32 v170, v2, v3
	v_cvt_pk_f16_f32 v171, v4, v5
	v_mul_f32_e32 v150, v7, v7
	v_mul_f32_e32 v151, v9, v9
	v_fmac_f32_e32 v150, v6, v6
	v_fmac_f32_e32 v151, v8, v8
	v_add_f32_e32 v152, v150, v151
	v_add_f32_e32 v160, v160, v152
	v_cvt_pk_f16_f32 v172, v6, v7
	v_cvt_pk_f16_f32 v173, v8, v9
	v_mul_f32_e32 v150, v11, v11
	v_mul_f32_e32 v151, v13, v13
	v_fmac_f32_e32 v150, v10, v10
	v_fmac_f32_e32 v151, v12, v12
	v_add_f32_e32 v152, v150, v151
	v_add_f32_e32 v160, v160, v152
	v_cvt_pk_f16_f32 v174, v10, v11
	v_cvt_pk_f16_f32 v175, v12, v13
	v_mul_f32_e32 v150, v15, v15
	v_mul_f32_e32 v151, v17, v17
	v_fmac_f32_e32 v150, v14, v14
	v_fmac_f32_e32 v151, v16, v16
	v_add_f32_e32 v152, v150, v151
	v_add_f32_e32 v160, v160, v152
	v_cvt_pk_f16_f32 v176, v14, v15
	v_cvt_pk_f16_f32 v177, v16, v17
	global_store_dwordx2 v144, v[170:171], s[10:11]
	global_store_dwordx2 v144, v[172:173], s[10:11] offset:512
	global_store_dwordx2 v144, v[174:175], s[10:11] offset:1024
	global_store_dwordx2 v144, v[176:177], s[10:11] offset:1536
	v_mul_f32_e32 v150, v19, v19
	v_mul_f32_e32 v151, v21, v21
	v_fmac_f32_e32 v150, v18, v18
	v_fmac_f32_e32 v151, v20, v20
	v_add_f32_e32 v161, v150, v151
	v_cvt_pk_f16_f32 v178, v18, v19
	v_cvt_pk_f16_f32 v179, v20, v21
	v_mul_f32_e32 v150, v23, v23
	v_mul_f32_e32 v151, v25, v25
	v_fmac_f32_e32 v150, v22, v22
	v_fmac_f32_e32 v151, v24, v24
	v_add_f32_e32 v152, v150, v151
	v_add_f32_e32 v161, v161, v152
	v_cvt_pk_f16_f32 v180, v22, v23
	v_cvt_pk_f16_f32 v181, v24, v25
	v_mul_f32_e32 v150, v27, v27
	v_mul_f32_e32 v151, v29, v29
	v_fmac_f32_e32 v150, v26, v26
	v_fmac_f32_e32 v151, v28, v28
	v_add_f32_e32 v152, v150, v151
	v_add_f32_e32 v161, v161, v152
	v_cvt_pk_f16_f32 v182, v26, v27
	v_cvt_pk_f16_f32 v183, v28, v29
	v_mul_f32_e32 v150, v31, v31
	v_mul_f32_e32 v151, v33, v33
	v_fmac_f32_e32 v150, v30, v30
	v_fmac_f32_e32 v151, v32, v32
	v_add_f32_e32 v152, v150, v151
	v_add_f32_e32 v161, v161, v152
; __device__ void p0_xconv(const Args& a) {
;     ...
;         for (int r = 0; r < 4; ++r) {
;             const int row = row0 + r * nwv;
;             if (row < MROWS) {
;                 float ss = 0.f;
; #pragma unroll
;                 for (int i = 0; i < 4; ++i) {
;                     const f32x4 x = v[r][i];
;                     ss += (x[0] * x[0] + x[1] * x[1]) + (x[2] * x[2] + x[3] * x[3]);
;                     f16x4 h; h[0] = (f16)x[0]; h[1] = (f16)x[1]; h[2] = (f16)x[2]; h[3] = (f16)x[3];
;                     *(f16x4*)(XH + (size_t)row * DM + i * 256 + lane * 4) = h;
;                 }
; #pragma unroll
;                 for (int o = 1; o < 64; o <<= 1) ss += __shfl_xor(ss, o);
;                 if (lane < 16) SS[(size_t)row * 16 + lane] = (lane == 0) ? ss : 0.f;
;             }
	v_cvt_pk_f16_f32 v184, v30, v31
	v_cvt_pk_f16_f32 v185, v32, v33
	global_store_dwordx2 v145, v[178:179], s[10:11]
	global_store_dwordx2 v145, v[180:181], s[10:11] offset:512
	global_store_dwordx2 v145, v[182:183], s[10:11] offset:1024
	global_store_dwordx2 v145, v[184:185], s[10:11] offset:1536
	v_mul_f32_e32 v150, v35, v35
	v_mul_f32_e32 v151, v37, v37
	v_fmac_f32_e32 v150, v34, v34
	v_fmac_f32_e32 v151, v36, v36
	v_add_f32_e32 v162, v150, v151
	v_cvt_pk_f16_f32 v170, v34, v35
	v_cvt_pk_f16_f32 v171, v36, v37
	v_mul_f32_e32 v150, v39, v39
	v_mul_f32_e32 v151, v41, v41
	v_fmac_f32_e32 v150, v38, v38
	v_fmac_f32_e32 v151, v40, v40
	v_add_f32_e32 v152, v150, v151
	v_add_f32_e32 v162, v162, v152
	v_cvt_pk_f16_f32 v172, v38, v39
	v_cvt_pk_f16_f32 v173, v40, v41
	v_mul_f32_e32 v150, v43, v43
	v_mul_f32_e32 v151, v45, v45
	v_fmac_f32_e32 v150, v42, v42
	v_fmac_f32_e32 v151, v44, v44
	v_add_f32_e32 v152, v150, v151
	v_add_f32_e32 v162, v162, v152
	v_cvt_pk_f16_f32 v174, v42, v43
	v_cvt_pk_f16_f32 v175, v44, v45
	v_mul_f32_e32 v150, v47, v47
	v_mul_f32_e32 v151, v49, v49
	v_fmac_f32_e32 v150, v46, v46
	v_fmac_f32_e32 v151, v48, v48
	v_add_f32_e32 v152, v150, v151
	v_add_f32_e32 v162, v162, v152
	v_cvt_pk_f16_f32 v176, v46, v47
	v_cvt_pk_f16_f32 v177, v48, v49
	global_store_dwordx2 v146, v[170:171], s[10:11]
	global_store_dwordx2 v146, v[172:173], s[10:11] offset:512
	global_store_dwordx2 v146, v[174:175], s[10:11] offset:1024
	global_store_dwordx2 v146, v[176:177], s[10:11] offset:1536
	v_mul_f32_e32 v150, v51, v51
	v_mul_f32_e32 v151, v53, v53
	v_fmac_f32_e32 v150, v50, v50
	v_fmac_f32_e32 v151, v52, v52
	v_add_f32_e32 v163, v150, v151
	v_cvt_pk_f16_f32 v178, v50, v51
	v_cvt_pk_f16_f32 v179, v52, v53
	v_mul_f32_e32 v150, v55, v55
	v_mul_f32_e32 v151, v57, v57
	v_fmac_f32_e32 v150, v54, v54
	v_fmac_f32_e32 v151, v56, v56
	v_add_f32_e32 v152, v150, v151
	v_add_f32_e32 v163, v163, v152
	v_cvt_pk_f16_f32 v180, v54, v55
	v_cvt_pk_f16_f32 v181, v56, v57
	v_mul_f32_e32 v150, v59, v59
	v_mul_f32_e32 v151, v61, v61
	v_fmac_f32_e32 v150, v58, v58
	v_fmac_f32_e32 v151, v60, v60
	v_add_f32_e32 v152, v150, v151
	v_add_f32_e32 v163, v163, v152
	v_cvt_pk_f16_f32 v182, v58, v59
	v_cvt_pk_f16_f32 v183, v60, v61
	v_mul_f32_e32 v150, v63, v63
	v_mul_f32_e32 v151, v65, v65
	v_fmac_f32_e32 v150, v62, v62
	v_fmac_f32_e32 v151, v64, v64
	v_add_f32_e32 v152, v150, v151
	v_add_f32_e32 v163, v163, v152
	v_cvt_pk_f16_f32 v184, v62, v63
	v_cvt_pk_f16_f32 v185, v64, v65
	global_store_dwordx2 v147, v[178:179], s[10:11]
	global_store_dwordx2 v147, v[180:181], s[10:11] offset:512
	global_store_dwordx2 v147, v[182:183], s[10:11] offset:1024
	global_store_dwordx2 v147, v[184:185], s[10:11] offset:1536
	ds_bpermute_b32 v164, v130, v160
	ds_bpermute_b32 v165, v130, v161
	ds_bpermute_b32 v166, v130, v162
	ds_bpermute_b32 v167, v130, v163
	s_waitcnt lgkmcnt(0)
	v_add_f32_e32 v160, v160, v164
	v_add_f32_e32 v161, v161, v165
	v_add_f32_e32 v162, v162, v166
	v_add_f32_e32 v163, v163, v167
	ds_bpermute_b32 v164, v131, v160
	ds_bpermute_b32 v165, v131, v161
	ds_bpermute_b32 v166, v131, v162
	ds_bpermute_b32 v167, v131, v163
	s_waitcnt lgkmcnt(0)
	v_add_f32_e32 v160, v160, v164
	v_add_f32_e32 v161, v161, v165
	v_add_f32_e32 v162, v162, v166
	v_add_f32_e32 v163, v163, v167
	ds_bpermute_b32 v164, v132, v160
	ds_bpermute_b32 v165, v132, v161
	ds_bpermute_b32 v166, v132, v162
	ds_bpermute_b32 v167, v132, v163
	s_waitcnt lgkmcnt(0)
	v_add_f32_e32 v160, v160, v164
	v_add_f32_e32 v161, v161, v165
	v_add_f32_e32 v162, v162, v166
	v_add_f32_e32 v163, v163, v167
	ds_bpermute_b32 v164, v133, v160
	ds_bpermute_b32 v165, v133, v161
	ds_bpermute_b32 v166, v133, v162
	ds_bpermute_b32 v167, v133, v163
	s_waitcnt lgkmcnt(0)
	v_add_f32_e32 v160, v160, v164
	v_add_f32_e32 v161, v161, v165
	v_add_f32_e32 v162, v162, v166
	v_add_f32_e32 v163, v163, v167
	ds_bpermute_b32 v164, v134, v160
	ds_bpermute_b32 v165, v134, v161
	ds_bpermute_b32 v166, v134, v162
	ds_bpermute_b32 v167, v134, v163
	s_waitcnt lgkmcnt(0)
	v_add_f32_e32 v160, v160, v164
	v_add_f32_e32 v161, v161, v165
	v_add_f32_e32 v162, v162, v166
	v_add_f32_e32 v163, v163, v167
	ds_bpermute_b32 v164, v135, v160
	ds_bpermute_b32 v165, v135, v161
	ds_bpermute_b32 v166, v135, v162
	ds_bpermute_b32 v167, v135, v163
	s_waitcnt lgkmcnt(0)
	v_add_f32_e32 v160, v160, v164
	v_add_f32_e32 v161, v161, v165
	v_add_f32_e32 v162, v162, v166
	v_add_f32_e32 v163, v163, v167
	v_cndmask_b32_e64 v164, 0, v160, s[12:13]
	v_cndmask_b32_e64 v165, 0, v161, s[12:13]
	v_cndmask_b32_e64 v166, 0, v162, s[12:13]
	v_cndmask_b32_e64 v167, 0, v163, s[12:13]
	s_mov_b64 exec, 0xffff
	global_store_dword v186, v164, s[6:7]
	global_store_dword v187, v165, s[6:7]
	global_store_dword v188, v166, s[6:7]
	global_store_dword v189, v167, s[6:7]
	s_mov_b64 exec, -1
	s_barrier
; __device__ void p0_xconv(const Args& a) {
;     ...
;     for (int row0 = (int)blockIdx.x * 8 + wv; row0 < MROWS; row0 += 4 * nwv) {
;         f32x4 v[4][4];
; #pragma unroll
;         for (int r = 0; r < 4; ++r) {
;             const int row = row0 + r * nwv;
;             if (row < MROWS) {
;                 const float* src = (row < ROWS_PROMPT) ? a.x_prompt + (size_t)row * DM : a.x_sample + (size_t)(row - ROWS_PROMPT) * DM;
; #pragma unroll
;                 for (int i = 0; i < 4; ++i) v[r][i] = __builtin_nontemporal_load((const f32x4*)(src + i * 256 + lane * 4));
;             }
;         }
; #pragma unroll
;         for (int r = 0; r < 4; ++r) {
;             const int row = row0 + r * nwv;
;             if (row < MROWS) {
;                 float ss = 0.f;
; #pragma unroll
;                 for (int i = 0; i < 4; ++i) {
;                     const f32x4 x = v[r][i];
;                     ss += (x[0] * x[0] + x[1] * x[1]) + (x[2] * x[2] + x[3] * x[3]);
;                     f16x4 h; h[0] = (f16)x[0]; h[1] = (f16)x[1]; h[2] = (f16)x[2]; h[3] = (f16)x[3];
;                     *(f16x4*)(XH + (size_t)row * DM + i * 256 + lane * 4) = h;
;                 }
; #pragma unroll
;                 for (int o = 1; o < 64; o <<= 1) ss += __shfl_xor(ss, o);
;                 if (lane < 16) SS[(size_t)row * 16 + lane] = (lane == 0) ? ss : 0.f;
	s_add_i32 s6, s3, 0x6000
	s_lshl_b32 s6, s6, 12
	s_add_u32 s4, s18, s6
	s_addc_u32 s5, s19, 0
	global_load_dwordx4 v[2:5], v140, s[4:5] nt
	global_load_dwordx4 v[6:9], v140, s[4:5] offset:1024 nt
	global_load_dwordx4 v[10:13], v140, s[4:5] offset:2048 nt
	global_load_dwordx4 v[14:17], v140, s[4:5] offset:3072 nt
	global_load_dwordx4 v[18:21], v141, s[4:5] nt
	global_load_dwordx4 v[22:25], v141, s[4:5] offset:1024 nt
	global_load_dwordx4 v[26:29], v141, s[4:5] offset:2048 nt
	global_load_dwordx4 v[30:33], v141, s[4:5] offset:3072 nt
	global_load_dwordx4 v[34:37], v142, s[4:5] nt
	global_load_dwordx4 v[38:41], v142, s[4:5] offset:1024 nt
	global_load_dwordx4 v[42:45], v142, s[4:5] offset:2048 nt
	global_load_dwordx4 v[46:49], v142, s[4:5] offset:3072 nt
	global_load_dwordx4 v[50:53], v143, s[4:5] nt
	global_load_dwordx4 v[54:57], v143, s[4:5] offset:1024 nt
	global_load_dwordx4 v[58:61], v143, s[4:5] offset:2048 nt
	global_load_dwordx4 v[62:65], v143, s[4:5] offset:3072 nt
	s_waitcnt vmcnt(36)
	s_add_i32 s6, s3, 0x9000
	s_lshl_b32 s7, s6, 11
	s_add_u32 s10, s40, s7
	s_addc_u32 s11, s41, 0
	s_lshl_b32 s7, s6, 6
	s_add_u32 s6, s40, s7
	s_addc_u32 s7, s41, 0
	s_add_u32 s6, s6, 0x1f800000
	s_addc_u32 s7, s7, 0
	v_mul_f32_e32 v150, v67, v67
	v_mul_f32_e32 v151, v69, v69
	v_fmac_f32_e32 v150, v66, v66
	v_fmac_f32_e32 v151, v68, v68
	v_add_f32_e32 v160, v150, v151
	v_cvt_pk_f16_f32 v170, v66, v67
	v_cvt_pk_f16_f32 v171, v68, v69
	v_mul_f32_e32 v150, v71, v71
	v_mul_f32_e32 v151, v73, v73
	v_fmac_f32_e32 v150, v70, v70
	v_fmac_f32_e32 v151, v72, v72
	v_add_f32_e32 v152, v150, v151
	v_add_f32_e32 v160, v160, v152
	v_cvt_pk_f16_f32 v172, v70, v71
	v_cvt_pk_f16_f32 v173, v72, v73
	v_mul_f32_e32 v150, v75, v75
	v_mul_f32_e32 v151, v77, v77
	v_fmac_f32_e32 v150, v74, v74
	v_fmac_f32_e32 v151, v76, v76
	v_add_f32_e32 v152, v150, v151
	v_add_f32_e32 v160, v160, v152
	v_cvt_pk_f16_f32 v174, v74, v75
	v_cvt_pk_f16_f32 v175, v76, v77
	v_mul_f32_e32 v150, v79, v79
	v_mul_f32_e32 v151, v81, v81
	v_fmac_f32_e32 v150, v78, v78
	v_fmac_f32_e32 v151, v80, v80
	v_add_f32_e32 v152, v150, v151
	v_add_f32_e32 v160, v160, v152
	v_cvt_pk_f16_f32 v176, v78, v79
	v_cvt_pk_f16_f32 v177, v80, v81
	global_store_dwordx2 v144, v[170:171], s[10:11]
	global_store_dwordx2 v144, v[172:173], s[10:11] offset:512
	global_store_dwordx2 v144, v[174:175], s[10:11] offset:1024
	global_store_dwordx2 v144, v[176:177], s[10:11] offset:1536
	v_mul_f32_e32 v150, v83, v83
	v_mul_f32_e32 v151, v85, v85
	v_fmac_f32_e32 v150, v82, v82
	v_fmac_f32_e32 v151, v84, v84
	v_add_f32_e32 v161, v150, v151
	v_cvt_pk_f16_f32 v178, v82, v83
	v_cvt_pk_f16_f32 v179, v84, v85
	v_mul_f32_e32 v150, v87, v87
	v_mul_f32_e32 v151, v89, v89
	v_fmac_f32_e32 v150, v86, v86
	v_fmac_f32_e32 v151, v88, v88
	v_add_f32_e32 v152, v150, v151
	v_add_f32_e32 v161, v161, v152
	v_cvt_pk_f16_f32 v180, v86, v87
	v_cvt_pk_f16_f32 v181, v88, v89
	v_mul_f32_e32 v150, v91, v91
	v_mul_f32_e32 v151, v93, v93
	v_fmac_f32_e32 v150, v90, v90
	v_fmac_f32_e32 v151, v92, v92
	v_add_f32_e32 v152, v150, v151
	v_add_f32_e32 v161, v161, v152
	v_cvt_pk_f16_f32 v182, v90, v91
	v_cvt_pk_f16_f32 v183, v92, v93
	v_mul_f32_e32 v150, v95, v95
	v_mul_f32_e32 v151, v97, v97
	v_fmac_f32_e32 v150, v94, v94
	v_fmac_f32_e32 v151, v96, v96
	v_add_f32_e32 v152, v150, v151
	v_add_f32_e32 v161, v161, v152
	v_cvt_pk_f16_f32 v184, v94, v95
	v_cvt_pk_f16_f32 v185, v96, v97
	global_store_dwordx2 v145, v[178:179], s[10:11]
	global_store_dwordx2 v145, v[180:181], s[10:11] offset:512
	global_store_dwordx2 v145, v[182:183], s[10:11] offset:1024
	global_store_dwordx2 v145, v[184:185], s[10:11] offset:1536
	v_mul_f32_e32 v150, v99, v99
	v_mul_f32_e32 v151, v101, v101
	v_fmac_f32_e32 v150, v98, v98
	v_fmac_f32_e32 v151, v100, v100
	v_add_f32_e32 v162, v150, v151
	v_cvt_pk_f16_f32 v170, v98, v99
	v_cvt_pk_f16_f32 v171, v100, v101
	v_mul_f32_e32 v150, v103, v103
	v_mul_f32_e32 v151, v105, v105
	v_fmac_f32_e32 v150, v102, v102
	v_fmac_f32_e32 v151, v104, v104
	v_add_f32_e32 v152, v150, v151
	v_add_f32_e32 v162, v162, v152
	v_cvt_pk_f16_f32 v172, v102, v103
	v_cvt_pk_f16_f32 v173, v104, v105
	v_mul_f32_e32 v150, v107, v107
	v_mul_f32_e32 v151, v109, v109
	v_fmac_f32_e32 v150, v106, v106
	v_fmac_f32_e32 v151, v108, v108
	v_add_f32_e32 v152, v150, v151
	v_add_f32_e32 v162, v162, v152
	v_cvt_pk_f16_f32 v174, v106, v107
	v_cvt_pk_f16_f32 v175, v108, v109
	v_mul_f32_e32 v150, v111, v111
	v_mul_f32_e32 v151, v113, v113
	v_fmac_f32_e32 v150, v110, v110
	v_fmac_f32_e32 v151, v112, v112
	v_add_f32_e32 v152, v150, v151
	v_add_f32_e32 v162, v162, v152
	v_cvt_pk_f16_f32 v176, v110, v111
	v_cvt_pk_f16_f32 v177, v112, v113
	global_store_dwordx2 v146, v[170:171], s[10:11]
	global_store_dwordx2 v146, v[172:173], s[10:11] offset:512
	global_store_dwordx2 v146, v[174:175], s[10:11] offset:1024
	global_store_dwordx2 v146, v[176:177], s[10:11] offset:1536
	v_mul_f32_e32 v150, v115, v115
	v_mul_f32_e32 v151, v117, v117
	v_fmac_f32_e32 v150, v114, v114
	v_fmac_f32_e32 v151, v116, v116
	v_add_f32_e32 v163, v150, v151
	v_cvt_pk_f16_f32 v178, v114, v115
	v_cvt_pk_f16_f32 v179, v116, v117
	v_mul_f32_e32 v150, v119, v119
	v_mul_f32_e32 v151, v121, v121
	v_fmac_f32_e32 v150, v118, v118
	v_fmac_f32_e32 v151, v120, v120
	v_add_f32_e32 v152, v150, v151
	v_add_f32_e32 v163, v163, v152
	v_cvt_pk_f16_f32 v180, v118, v119
	v_cvt_pk_f16_f32 v181, v120, v121
	v_mul_f32_e32 v150, v123, v123
	v_mul_f32_e32 v151, v125, v125
	v_fmac_f32_e32 v150, v122, v122
	v_fmac_f32_e32 v151, v124, v124
	v_add_f32_e32 v152, v150, v151
	v_add_f32_e32 v163, v163, v152
	v_cvt_pk_f16_f32 v182, v122, v123
	v_cvt_pk_f16_f32 v183, v124, v125
	v_mul_f32_e32 v150, v127, v127
	v_mul_f32_e32 v151, v129, v129
	v_fmac_f32_e32 v150, v126, v126
	v_fmac_f32_e32 v151, v128, v128
	v_add_f32_e32 v152, v150, v151
	v_add_f32_e32 v163, v163, v152
	v_cvt_pk_f16_f32 v184, v126, v127
	v_cvt_pk_f16_f32 v185, v128, v129
	global_store_dwordx2 v147, v[178:179], s[10:11]
	global_store_dwordx2 v147, v[180:181], s[10:11] offset:512
	global_store_dwordx2 v147, v[182:183], s[10:11] offset:1024
	global_store_dwordx2 v147, v[184:185], s[10:11] offset:1536
	ds_bpermute_b32 v164, v130, v160
	ds_bpermute_b32 v165, v130, v161
	ds_bpermute_b32 v166, v130, v162
	ds_bpermute_b32 v167, v130, v163
	s_waitcnt lgkmcnt(0)
; __device__ void p0_xconv(const Args& a) {
;     ...
;     for (int row0 = (int)blockIdx.x * 8 + wv; row0 < MROWS; row0 += 4 * nwv) {
;         f32x4 v[4][4];
; #pragma unroll
;         for (int r = 0; r < 4; ++r) {
;             const int row = row0 + r * nwv;
;             if (row < MROWS) {
;                 const float* src = (row < ROWS_PROMPT) ? a.x_prompt + (size_t)row * DM : a.x_sample + (size_t)(row - ROWS_PROMPT) * DM;
; #pragma unroll
;                 for (int i = 0; i < 4; ++i) v[r][i] = __builtin_nontemporal_load((const f32x4*)(src + i * 256 + lane * 4));
;             }
;         }
; #pragma unroll
;         for (int r = 0; r < 4; ++r) {
;             const int row = row0 + r * nwv;
;             if (row < MROWS) {
;                 float ss = 0.f;
; #pragma unroll
;                 for (int i = 0; i < 4; ++i) {
;                     const f32x4 x = v[r][i];
;                     ss += (x[0] * x[0] + x[1] * x[1]) + (x[2] * x[2] + x[3] * x[3]);
;                     f16x4 h; h[0] = (f16)x[0]; h[1] = (f16)x[1]; h[2] = (f16)x[2]; h[3] = (f16)x[3];
;                     *(f16x4*)(XH + (size_t)row * DM + i * 256 + lane * 4) = h;
;                 }
; #pragma unroll
;                 for (int o = 1; o < 64; o <<= 1) ss += __shfl_xor(ss, o);
;                 if (lane < 16) SS[(size_t)row * 16 + lane] = (lane == 0) ? ss : 0.f;
	v_add_f32_e32 v160, v160, v164
	v_add_f32_e32 v161, v161, v165
	v_add_f32_e32 v162, v162, v166
	v_add_f32_e32 v163, v163, v167
	ds_bpermute_b32 v164, v131, v160
	ds_bpermute_b32 v165, v131, v161
	ds_bpermute_b32 v166, v131, v162
	ds_bpermute_b32 v167, v131, v163
	s_waitcnt lgkmcnt(0)
	v_add_f32_e32 v160, v160, v164
	v_add_f32_e32 v161, v161, v165
	v_add_f32_e32 v162, v162, v166
	v_add_f32_e32 v163, v163, v167
	ds_bpermute_b32 v164, v132, v160
	ds_bpermute_b32 v165, v132, v161
	ds_bpermute_b32 v166, v132, v162
	ds_bpermute_b32 v167, v132, v163
	s_waitcnt lgkmcnt(0)
	v_add_f32_e32 v160, v160, v164
	v_add_f32_e32 v161, v161, v165
	v_add_f32_e32 v162, v162, v166
	v_add_f32_e32 v163, v163, v167
	ds_bpermute_b32 v164, v133, v160
	ds_bpermute_b32 v165, v133, v161
	ds_bpermute_b32 v166, v133, v162
	ds_bpermute_b32 v167, v133, v163
	s_waitcnt lgkmcnt(0)
	v_add_f32_e32 v160, v160, v164
	v_add_f32_e32 v161, v161, v165
	v_add_f32_e32 v162, v162, v166
	v_add_f32_e32 v163, v163, v167
	ds_bpermute_b32 v164, v134, v160
	ds_bpermute_b32 v165, v134, v161
	ds_bpermute_b32 v166, v134, v162
	ds_bpermute_b32 v167, v134, v163
	s_waitcnt lgkmcnt(0)
	v_add_f32_e32 v160, v160, v164
	v_add_f32_e32 v161, v161, v165
	v_add_f32_e32 v162, v162, v166
	v_add_f32_e32 v163, v163, v167
	ds_bpermute_b32 v164, v135, v160
	ds_bpermute_b32 v165, v135, v161
	ds_bpermute_b32 v166, v135, v162
	ds_bpermute_b32 v167, v135, v163
	s_waitcnt lgkmcnt(0)
	v_add_f32_e32 v160, v160, v164
	v_add_f32_e32 v161, v161, v165
	v_add_f32_e32 v162, v162, v166
	v_add_f32_e32 v163, v163, v167
	v_cndmask_b32_e64 v164, 0, v160, s[12:13]
	v_cndmask_b32_e64 v165, 0, v161, s[12:13]
	v_cndmask_b32_e64 v166, 0, v162, s[12:13]
	v_cndmask_b32_e64 v167, 0, v163, s[12:13]
	s_mov_b64 exec, 0xffff
	global_store_dword v186, v164, s[6:7]
	global_store_dword v187, v165, s[6:7]
	global_store_dword v188, v166, s[6:7]
	global_store_dword v189, v167, s[6:7]
	s_mov_b64 exec, -1
	s_add_i32 s6, s3, 0x7000
	s_lshl_b32 s6, s6, 12
	s_add_u32 s4, s18, s6
	s_addc_u32 s5, s19, 0
	global_load_dwordx4 v[66:69], v140, s[4:5] nt
	global_load_dwordx4 v[70:73], v140, s[4:5] offset:1024 nt
	global_load_dwordx4 v[74:77], v140, s[4:5] offset:2048 nt
	global_load_dwordx4 v[78:81], v140, s[4:5] offset:3072 nt
	global_load_dwordx4 v[82:85], v141, s[4:5] nt
	global_load_dwordx4 v[86:89], v141, s[4:5] offset:1024 nt
	global_load_dwordx4 v[90:93], v141, s[4:5] offset:2048 nt
	global_load_dwordx4 v[94:97], v141, s[4:5] offset:3072 nt
	global_load_dwordx4 v[98:101], v142, s[4:5] nt
	global_load_dwordx4 v[102:105], v142, s[4:5] offset:1024 nt
	global_load_dwordx4 v[106:109], v142, s[4:5] offset:2048 nt
	global_load_dwordx4 v[110:113], v142, s[4:5] offset:3072 nt
	global_load_dwordx4 v[114:117], v143, s[4:5] nt
	global_load_dwordx4 v[118:121], v143, s[4:5] offset:1024 nt
	global_load_dwordx4 v[122:125], v143, s[4:5] offset:2048 nt
	global_load_dwordx4 v[126:129], v143, s[4:5] offset:3072 nt
	s_waitcnt vmcnt(36)
	s_add_i32 s6, s3, 0xa000
	s_lshl_b32 s7, s6, 11
	s_add_u32 s10, s40, s7
	s_addc_u32 s11, s41, 0
	s_lshl_b32 s7, s6, 6
	s_add_u32 s6, s40, s7
	s_addc_u32 s7, s41, 0
	s_add_u32 s6, s6, 0x1f800000
	s_addc_u32 s7, s7, 0
	v_mul_f32_e32 v150, v3, v3
	v_mul_f32_e32 v151, v5, v5
	v_fmac_f32_e32 v150, v2, v2
	v_fmac_f32_e32 v151, v4, v4
	v_add_f32_e32 v160, v150, v151
	v_cvt_pk_f16_f32 v170, v2, v3
	v_cvt_pk_f16_f32 v171, v4, v5
	v_mul_f32_e32 v150, v7, v7
	v_mul_f32_e32 v151, v9, v9
	v_fmac_f32_e32 v150, v6, v6
	v_fmac_f32_e32 v151, v8, v8
	v_add_f32_e32 v152, v150, v151
	v_add_f32_e32 v160, v160, v152
	v_cvt_pk_f16_f32 v172, v6, v7
	v_cvt_pk_f16_f32 v173, v8, v9
	v_mul_f32_e32 v150, v11, v11
	v_mul_f32_e32 v151, v13, v13
	v_fmac_f32_e32 v150, v10, v10
	v_fmac_f32_e32 v151, v12, v12
	v_add_f32_e32 v152, v150, v151
	v_add_f32_e32 v160, v160, v152
	v_cvt_pk_f16_f32 v174, v10, v11
	v_cvt_pk_f16_f32 v175, v12, v13
	v_mul_f32_e32 v150, v15, v15
	v_mul_f32_e32 v151, v17, v17
	v_fmac_f32_e32 v150, v14, v14
	v_fmac_f32_e32 v151, v16, v16
	v_add_f32_e32 v152, v150, v151
	v_add_f32_e32 v160, v160, v152
	v_cvt_pk_f16_f32 v176, v14, v15
	v_cvt_pk_f16_f32 v177, v16, v17
	global_store_dwordx2 v144, v[170:171], s[10:11]
	global_store_dwordx2 v144, v[172:173], s[10:11] offset:512
	global_store_dwordx2 v144, v[174:175], s[10:11] offset:1024
	global_store_dwordx2 v144, v[176:177], s[10:11] offset:1536
	v_mul_f32_e32 v150, v19, v19
	v_mul_f32_e32 v151, v21, v21
	v_fmac_f32_e32 v150, v18, v18
	v_fmac_f32_e32 v151, v20, v20
	v_add_f32_e32 v161, v150, v151
	v_cvt_pk_f16_f32 v178, v18, v19
	v_cvt_pk_f16_f32 v179, v20, v21
	v_mul_f32_e32 v150, v23, v23
	v_mul_f32_e32 v151, v25, v25
	v_fmac_f32_e32 v150, v22, v22
	v_fmac_f32_e32 v151, v24, v24
	v_add_f32_e32 v152, v150, v151
	v_add_f32_e32 v161, v161, v152
	v_cvt_pk_f16_f32 v180, v22, v23
	v_cvt_pk_f16_f32 v181, v24, v25
	v_mul_f32_e32 v150, v27, v27
	v_mul_f32_e32 v151, v29, v29
	v_fmac_f32_e32 v150, v26, v26
	v_fmac_f32_e32 v151, v28, v28
	v_add_f32_e32 v152, v150, v151
	v_add_f32_e32 v161, v161, v152
	v_cvt_pk_f16_f32 v182, v26, v27
	v_cvt_pk_f16_f32 v183, v28, v29
	v_mul_f32_e32 v150, v31, v31
	v_mul_f32_e32 v151, v33, v33
	v_fmac_f32_e32 v150, v30, v30
	v_fmac_f32_e32 v151, v32, v32
	v_add_f32_e32 v152, v150, v151
	v_add_f32_e32 v161, v161, v152
	v_cvt_pk_f16_f32 v184, v30, v31
	v_cvt_pk_f16_f32 v185, v32, v33
	global_store_dwordx2 v145, v[178:179], s[10:11]
	global_store_dwordx2 v145, v[180:181], s[10:11] offset:512
	global_store_dwordx2 v145, v[182:183], s[10:11] offset:1024
	global_store_dwordx2 v145, v[184:185], s[10:11] offset:1536
	v_mul_f32_e32 v150, v35, v35
	v_mul_f32_e32 v151, v37, v37
	v_fmac_f32_e32 v150, v34, v34
; __device__ void p0_xconv(const Args& a) {
;     ...
;         for (int r = 0; r < 4; ++r) {
;             const int row = row0 + r * nwv;
;             if (row < MROWS) {
;                 float ss = 0.f;
; #pragma unroll
;                 for (int i = 0; i < 4; ++i) {
;                     const f32x4 x = v[r][i];
;                     ss += (x[0] * x[0] + x[1] * x[1]) + (x[2] * x[2] + x[3] * x[3]);
;                     f16x4 h; h[0] = (f16)x[0]; h[1] = (f16)x[1]; h[2] = (f16)x[2]; h[3] = (f16)x[3];
;                     *(f16x4*)(XH + (size_t)row * DM + i * 256 + lane * 4) = h;
;                 }
; #pragma unroll
;                 for (int o = 1; o < 64; o <<= 1) ss += __shfl_xor(ss, o);
;                 if (lane < 16) SS[(size_t)row * 16 + lane] = (lane == 0) ? ss : 0.f;
	v_fmac_f32_e32 v151, v36, v36
	v_add_f32_e32 v162, v150, v151
	v_cvt_pk_f16_f32 v170, v34, v35
	v_cvt_pk_f16_f32 v171, v36, v37
	v_mul_f32_e32 v150, v39, v39
	v_mul_f32_e32 v151, v41, v41
	v_fmac_f32_e32 v150, v38, v38
	v_fmac_f32_e32 v151, v40, v40
	v_add_f32_e32 v152, v150, v151
	v_add_f32_e32 v162, v162, v152
	v_cvt_pk_f16_f32 v172, v38, v39
	v_cvt_pk_f16_f32 v173, v40, v41
	v_mul_f32_e32 v150, v43, v43
	v_mul_f32_e32 v151, v45, v45
	v_fmac_f32_e32 v150, v42, v42
	v_fmac_f32_e32 v151, v44, v44
	v_add_f32_e32 v152, v150, v151
	v_add_f32_e32 v162, v162, v152
	v_cvt_pk_f16_f32 v174, v42, v43
	v_cvt_pk_f16_f32 v175, v44, v45
	v_mul_f32_e32 v150, v47, v47
	v_mul_f32_e32 v151, v49, v49
	v_fmac_f32_e32 v150, v46, v46
	v_fmac_f32_e32 v151, v48, v48
	v_add_f32_e32 v152, v150, v151
	v_add_f32_e32 v162, v162, v152
	v_cvt_pk_f16_f32 v176, v46, v47
	v_cvt_pk_f16_f32 v177, v48, v49
	global_store_dwordx2 v146, v[170:171], s[10:11]
	global_store_dwordx2 v146, v[172:173], s[10:11] offset:512
	global_store_dwordx2 v146, v[174:175], s[10:11] offset:1024
	global_store_dwordx2 v146, v[176:177], s[10:11] offset:1536
	v_mul_f32_e32 v150, v51, v51
	v_mul_f32_e32 v151, v53, v53
	v_fmac_f32_e32 v150, v50, v50
	v_fmac_f32_e32 v151, v52, v52
	v_add_f32_e32 v163, v150, v151
	v_cvt_pk_f16_f32 v178, v50, v51
	v_cvt_pk_f16_f32 v179, v52, v53
	v_mul_f32_e32 v150, v55, v55
	v_mul_f32_e32 v151, v57, v57
	v_fmac_f32_e32 v150, v54, v54
	v_fmac_f32_e32 v151, v56, v56
	v_add_f32_e32 v152, v150, v151
	v_add_f32_e32 v163, v163, v152
	v_cvt_pk_f16_f32 v180, v54, v55
	v_cvt_pk_f16_f32 v181, v56, v57
	v_mul_f32_e32 v150, v59, v59
	v_mul_f32_e32 v151, v61, v61
	v_fmac_f32_e32 v150, v58, v58
	v_fmac_f32_e32 v151, v60, v60
	v_add_f32_e32 v152, v150, v151
	v_add_f32_e32 v163, v163, v152
	v_cvt_pk_f16_f32 v182, v58, v59
	v_cvt_pk_f16_f32 v183, v60, v61
	v_mul_f32_e32 v150, v63, v63
	v_mul_f32_e32 v151, v65, v65
	v_fmac_f32_e32 v150, v62, v62
	v_fmac_f32_e32 v151, v64, v64
	v_add_f32_e32 v152, v150, v151
	v_add_f32_e32 v163, v163, v152
	v_cvt_pk_f16_f32 v184, v62, v63
	v_cvt_pk_f16_f32 v185, v64, v65
	global_store_dwordx2 v147, v[178:179], s[10:11]
	global_store_dwordx2 v147, v[180:181], s[10:11] offset:512
	global_store_dwordx2 v147, v[182:183], s[10:11] offset:1024
	global_store_dwordx2 v147, v[184:185], s[10:11] offset:1536
	ds_bpermute_b32 v164, v130, v160
	ds_bpermute_b32 v165, v130, v161
	ds_bpermute_b32 v166, v130, v162
	ds_bpermute_b32 v167, v130, v163
	s_waitcnt lgkmcnt(0)
	v_add_f32_e32 v160, v160, v164
	v_add_f32_e32 v161, v161, v165
	v_add_f32_e32 v162, v162, v166
	v_add_f32_e32 v163, v163, v167
	ds_bpermute_b32 v164, v131, v160
	ds_bpermute_b32 v165, v131, v161
	ds_bpermute_b32 v166, v131, v162
	ds_bpermute_b32 v167, v131, v163
	s_waitcnt lgkmcnt(0)
	v_add_f32_e32 v160, v160, v164
	v_add_f32_e32 v161, v161, v165
	v_add_f32_e32 v162, v162, v166
	v_add_f32_e32 v163, v163, v167
	ds_bpermute_b32 v164, v132, v160
	ds_bpermute_b32 v165, v132, v161
	ds_bpermute_b32 v166, v132, v162
	ds_bpermute_b32 v167, v132, v163
	s_waitcnt lgkmcnt(0)
	v_add_f32_e32 v160, v160, v164
	v_add_f32_e32 v161, v161, v165
	v_add_f32_e32 v162, v162, v166
	v_add_f32_e32 v163, v163, v167
	ds_bpermute_b32 v164, v133, v160
	ds_bpermute_b32 v165, v133, v161
	ds_bpermute_b32 v166, v133, v162
	ds_bpermute_b32 v167, v133, v163
	s_waitcnt lgkmcnt(0)
	v_add_f32_e32 v160, v160, v164
	v_add_f32_e32 v161, v161, v165
	v_add_f32_e32 v162, v162, v166
	v_add_f32_e32 v163, v163, v167
	ds_bpermute_b32 v164, v134, v160
	ds_bpermute_b32 v165, v134, v161
	ds_bpermute_b32 v166, v134, v162
	ds_bpermute_b32 v167, v134, v163
	s_waitcnt lgkmcnt(0)
	v_add_f32_e32 v160, v160, v164
	v_add_f32_e32 v161, v161, v165
	v_add_f32_e32 v162, v162, v166
	v_add_f32_e32 v163, v163, v167
	ds_bpermute_b32 v164, v135, v160
	ds_bpermute_b32 v165, v135, v161
	ds_bpermute_b32 v166, v135, v162
	ds_bpermute_b32 v167, v135, v163
	s_waitcnt lgkmcnt(0)
	v_add_f32_e32 v160, v160, v164
	v_add_f32_e32 v161, v161, v165
	v_add_f32_e32 v162, v162, v166
	v_add_f32_e32 v163, v163, v167
	v_cndmask_b32_e64 v164, 0, v160, s[12:13]
	v_cndmask_b32_e64 v165, 0, v161, s[12:13]
	v_cndmask_b32_e64 v166, 0, v162, s[12:13]
	v_cndmask_b32_e64 v167, 0, v163, s[12:13]
	s_mov_b64 exec, 0xffff
	global_store_dword v186, v164, s[6:7]
	global_store_dword v187, v165, s[6:7]
	global_store_dword v188, v166, s[6:7]
	global_store_dword v189, v167, s[6:7]
	s_mov_b64 exec, -1
	s_waitcnt vmcnt(20)
; __device__ void p0_xconv(const Args& a) {
;     ...
;         for (int r = 0; r < 4; ++r) {
;             const int row = row0 + r * nwv;
;             if (row < MROWS) {
;                 float ss = 0.f;
; #pragma unroll
;                 for (int i = 0; i < 4; ++i) {
;                     const f32x4 x = v[r][i];
;                     ss += (x[0] * x[0] + x[1] * x[1]) + (x[2] * x[2] + x[3] * x[3]);
;                     f16x4 h; h[0] = (f16)x[0]; h[1] = (f16)x[1]; h[2] = (f16)x[2]; h[3] = (f16)x[3];
;                     *(f16x4*)(XH + (size_t)row * DM + i * 256 + lane * 4) = h;
;                 }
; #pragma unroll
;                 for (int o = 1; o < 64; o <<= 1) ss += __shfl_xor(ss, o);
;                 if (lane < 16) SS[(size_t)row * 16 + lane] = (lane == 0) ? ss : 0.f;
	s_add_i32 s6, s3, 0xb000
	s_lshl_b32 s7, s6, 11
	s_add_u32 s10, s40, s7
	s_addc_u32 s11, s41, 0
	s_lshl_b32 s7, s6, 6
	s_add_u32 s6, s40, s7
	s_addc_u32 s7, s41, 0
	s_add_u32 s6, s6, 0x1f800000
	s_addc_u32 s7, s7, 0
	v_mul_f32_e32 v150, v67, v67
	v_mul_f32_e32 v151, v69, v69
	v_fmac_f32_e32 v150, v66, v66
	v_fmac_f32_e32 v151, v68, v68
	v_add_f32_e32 v160, v150, v151
	v_cvt_pk_f16_f32 v170, v66, v67
	v_cvt_pk_f16_f32 v171, v68, v69
	v_mul_f32_e32 v150, v71, v71
	v_mul_f32_e32 v151, v73, v73
	v_fmac_f32_e32 v150, v70, v70
	v_fmac_f32_e32 v151, v72, v72
	v_add_f32_e32 v152, v150, v151
	v_add_f32_e32 v160, v160, v152
	v_cvt_pk_f16_f32 v172, v70, v71
	v_cvt_pk_f16_f32 v173, v72, v73
	v_mul_f32_e32 v150, v75, v75
	v_mul_f32_e32 v151, v77, v77
	v_fmac_f32_e32 v150, v74, v74
	v_fmac_f32_e32 v151, v76, v76
	v_add_f32_e32 v152, v150, v151
	v_add_f32_e32 v160, v160, v152
	v_cvt_pk_f16_f32 v174, v74, v75
	v_cvt_pk_f16_f32 v175, v76, v77
	v_mul_f32_e32 v150, v79, v79
	v_mul_f32_e32 v151, v81, v81
	v_fmac_f32_e32 v150, v78, v78
	v_fmac_f32_e32 v151, v80, v80
	v_add_f32_e32 v152, v150, v151
	v_add_f32_e32 v160, v160, v152
	v_cvt_pk_f16_f32 v176, v78, v79
	v_cvt_pk_f16_f32 v177, v80, v81
	global_store_dwordx2 v144, v[170:171], s[10:11]
	global_store_dwordx2 v144, v[172:173], s[10:11] offset:512
	global_store_dwordx2 v144, v[174:175], s[10:11] offset:1024
	global_store_dwordx2 v144, v[176:177], s[10:11] offset:1536
	v_mul_f32_e32 v150, v83, v83
	v_mul_f32_e32 v151, v85, v85
	v_fmac_f32_e32 v150, v82, v82
	v_fmac_f32_e32 v151, v84, v84
	v_add_f32_e32 v161, v150, v151
	v_cvt_pk_f16_f32 v178, v82, v83
	v_cvt_pk_f16_f32 v179, v84, v85
	v_mul_f32_e32 v150, v87, v87
	v_mul_f32_e32 v151, v89, v89
	v_fmac_f32_e32 v150, v86, v86
	v_fmac_f32_e32 v151, v88, v88
	v_add_f32_e32 v152, v150, v151
	v_add_f32_e32 v161, v161, v152
	v_cvt_pk_f16_f32 v180, v86, v87
	v_cvt_pk_f16_f32 v181, v88, v89
	v_mul_f32_e32 v150, v91, v91
	v_mul_f32_e32 v151, v93, v93
	v_fmac_f32_e32 v150, v90, v90
	v_fmac_f32_e32 v151, v92, v92
	v_add_f32_e32 v152, v150, v151
	v_add_f32_e32 v161, v161, v152
	v_cvt_pk_f16_f32 v182, v90, v91
	v_cvt_pk_f16_f32 v183, v92, v93
	v_mul_f32_e32 v150, v95, v95
	v_mul_f32_e32 v151, v97, v97
	v_fmac_f32_e32 v150, v94, v94
	v_fmac_f32_e32 v151, v96, v96
	v_add_f32_e32 v152, v150, v151
	v_add_f32_e32 v161, v161, v152
	v_cvt_pk_f16_f32 v184, v94, v95
	v_cvt_pk_f16_f32 v185, v96, v97
	global_store_dwordx2 v145, v[178:179], s[10:11]
	global_store_dwordx2 v145, v[180:181], s[10:11] offset:512
	global_store_dwordx2 v145, v[182:183], s[10:11] offset:1024
	global_store_dwordx2 v145, v[184:185], s[10:11] offset:1536
	v_mul_f32_e32 v150, v99, v99
	v_mul_f32_e32 v151, v101, v101
	v_fmac_f32_e32 v150, v98, v98
	v_fmac_f32_e32 v151, v100, v100
	v_add_f32_e32 v162, v150, v151
	v_cvt_pk_f16_f32 v170, v98, v99
	v_cvt_pk_f16_f32 v171, v100, v101
	v_mul_f32_e32 v150, v103, v103
	v_mul_f32_e32 v151, v105, v105
	v_fmac_f32_e32 v150, v102, v102
	v_fmac_f32_e32 v151, v104, v104
	v_add_f32_e32 v152, v150, v151
	v_add_f32_e32 v162, v162, v152
	v_cvt_pk_f16_f32 v172, v102, v103
	v_cvt_pk_f16_f32 v173, v104, v105
	v_mul_f32_e32 v150, v107, v107
	v_mul_f32_e32 v151, v109, v109
	v_fmac_f32_e32 v150, v106, v106
	v_fmac_f32_e32 v151, v108, v108
	v_add_f32_e32 v152, v150, v151
	v_add_f32_e32 v162, v162, v152
	v_cvt_pk_f16_f32 v174, v106, v107
	v_cvt_pk_f16_f32 v175, v108, v109
	v_mul_f32_e32 v150, v111, v111
	v_mul_f32_e32 v151, v113, v113
	v_fmac_f32_e32 v150, v110, v110
	v_fmac_f32_e32 v151, v112, v112
	v_add_f32_e32 v152, v150, v151
	v_add_f32_e32 v162, v162, v152
	v_cvt_pk_f16_f32 v176, v110, v111
	v_cvt_pk_f16_f32 v177, v112, v113
	global_store_dwordx2 v146, v[170:171], s[10:11]
	global_store_dwordx2 v146, v[172:173], s[10:11] offset:512
	global_store_dwordx2 v146, v[174:175], s[10:11] offset:1024
	global_store_dwordx2 v146, v[176:177], s[10:11] offset:1536
	v_mul_f32_e32 v150, v115, v115
	v_mul_f32_e32 v151, v117, v117
	v_fmac_f32_e32 v150, v114, v114
	v_fmac_f32_e32 v151, v116, v116
	v_add_f32_e32 v163, v150, v151
	v_cvt_pk_f16_f32 v178, v114, v115
	v_cvt_pk_f16_f32 v179, v116, v117
	v_mul_f32_e32 v150, v119, v119
	v_mul_f32_e32 v151, v121, v121
	v_fmac_f32_e32 v150, v118, v118
	v_fmac_f32_e32 v151, v120, v120
	v_add_f32_e32 v152, v150, v151
	v_add_f32_e32 v163, v163, v152
	v_cvt_pk_f16_f32 v180, v118, v119
	v_cvt_pk_f16_f32 v181, v120, v121
	v_mul_f32_e32 v150, v123, v123
	v_mul_f32_e32 v151, v125, v125
	v_fmac_f32_e32 v150, v122, v122
	v_fmac_f32_e32 v151, v124, v124
	v_add_f32_e32 v152, v150, v151
	v_add_f32_e32 v163, v163, v152
	v_cvt_pk_f16_f32 v182, v122, v123
	v_cvt_pk_f16_f32 v183, v124, v125
	v_mul_f32_e32 v150, v127, v127
	v_mul_f32_e32 v151, v129, v129
	v_fmac_f32_e32 v150, v126, v126
	v_fmac_f32_e32 v151, v128, v128
	v_add_f32_e32 v152, v150, v151
	v_add_f32_e32 v163, v163, v152
	v_cvt_pk_f16_f32 v184, v126, v127
	v_cvt_pk_f16_f32 v185, v128, v129
	global_store_dwordx2 v147, v[178:179], s[10:11]
	global_store_dwordx2 v147, v[180:181], s[10:11] offset:512
	global_store_dwordx2 v147, v[182:183], s[10:11] offset:1024
	global_store_dwordx2 v147, v[184:185], s[10:11] offset:1536
	ds_bpermute_b32 v164, v130, v160
	ds_bpermute_b32 v165, v130, v161
	ds_bpermute_b32 v166, v130, v162
	ds_bpermute_b32 v167, v130, v163
	s_waitcnt lgkmcnt(0)
; __device__ void p0_xconv(const Args& a) {
;     ...
;                 for (int o = 1; o < 64; o <<= 1) ss += __shfl_xor(ss, o);
;                 if (lane < 16) SS[(size_t)row * 16 + lane] = (lane == 0) ? ss : 0.f;
	v_add_f32_e32 v160, v160, v164
	v_add_f32_e32 v161, v161, v165
	v_add_f32_e32 v162, v162, v166
	v_add_f32_e32 v163, v163, v167
	ds_bpermute_b32 v164, v131, v160
	ds_bpermute_b32 v165, v131, v161
	ds_bpermute_b32 v166, v131, v162
	ds_bpermute_b32 v167, v131, v163
	s_waitcnt lgkmcnt(0)
	v_add_f32_e32 v160, v160, v164
	v_add_f32_e32 v161, v161, v165
	v_add_f32_e32 v162, v162, v166
	v_add_f32_e32 v163, v163, v167
	ds_bpermute_b32 v164, v132, v160
	ds_bpermute_b32 v165, v132, v161
	ds_bpermute_b32 v166, v132, v162
	ds_bpermute_b32 v167, v132, v163
	s_waitcnt lgkmcnt(0)
	v_add_f32_e32 v160, v160, v164
	v_add_f32_e32 v161, v161, v165
	v_add_f32_e32 v162, v162, v166
	v_add_f32_e32 v163, v163, v167
	ds_bpermute_b32 v164, v133, v160
	ds_bpermute_b32 v165, v133, v161
	ds_bpermute_b32 v166, v133, v162
	ds_bpermute_b32 v167, v133, v163
	s_waitcnt lgkmcnt(0)
	v_add_f32_e32 v160, v160, v164
	v_add_f32_e32 v161, v161, v165
	v_add_f32_e32 v162, v162, v166
	v_add_f32_e32 v163, v163, v167
	ds_bpermute_b32 v164, v134, v160
	ds_bpermute_b32 v165, v134, v161
	ds_bpermute_b32 v166, v134, v162
	ds_bpermute_b32 v167, v134, v163
	s_waitcnt lgkmcnt(0)
	v_add_f32_e32 v160, v160, v164
	v_add_f32_e32 v161, v161, v165
	v_add_f32_e32 v162, v162, v166
	v_add_f32_e32 v163, v163, v167
	ds_bpermute_b32 v164, v135, v160
	ds_bpermute_b32 v165, v135, v161
	ds_bpermute_b32 v166, v135, v162
	ds_bpermute_b32 v167, v135, v163
	s_waitcnt lgkmcnt(0)
	v_add_f32_e32 v160, v160, v164
	v_add_f32_e32 v161, v161, v165
	v_add_f32_e32 v162, v162, v166
	v_add_f32_e32 v163, v163, v167
	v_cndmask_b32_e64 v164, 0, v160, s[12:13]
	v_cndmask_b32_e64 v165, 0, v161, s[12:13]
	v_cndmask_b32_e64 v166, 0, v162, s[12:13]
	v_cndmask_b32_e64 v167, 0, v163, s[12:13]
	s_mov_b64 exec, 0xffff
	global_store_dword v186, v164, s[6:7]
	global_store_dword v187, v165, s[6:7]
	global_store_dword v188, v166, s[6:7]
	global_store_dword v189, v167, s[6:7]
	s_mov_b64 exec, -1
	s_setprio 0
	s_barrier
	s_branch .LBB0_112
